# grid barrier: generation taken from a barrier ordinal kept in a spare VGPR lane instead of two software integer divisions
# baseline (speedup 1.0000x reference)
_Z7enc_fwd4Args:
	v_writelane_b32 v255, 0, 61
	s_load_dword s83, s[0:1], 0xe0
	s_load_dwordx4 s[76:79], s[0:1], 0xc8
	s_add_u32 s4, s0, 0xe0
	v_writelane_b32 v252, s0, 0
	s_addc_u32 s5, s1, 0
	s_mov_b32 s3, s2
	v_writelane_b32 v252, s1, 1
	v_writelane_b32 v252, s4, 2
	s_waitcnt lgkmcnt(0)
	s_and_b32 s1, s83, 7
	s_mov_b32 s0, 0
	v_writelane_b32 v252, s5, 3
	s_cmp_lg_u32 s1, 0
	s_cbranch_scc1 .LBB0_2
	s_ashr_i32 s3, s2, 31
	s_lshr_b32 s3, s3, 29
	s_add_i32 s3, s2, s3
	s_and_b32 s4, s3, -8
	s_ashr_i32 s1, s83, 3
	s_sub_i32 s4, s2, s4
	s_mul_i32 s1, s1, s4
	s_ashr_i32 s3, s3, 3
	s_add_i32 s3, s1, s3

.LBB0_41:
	s_or_b64 exec, exec, s[6:7]
	v_readlane_b32 s100, v255, 61
	s_nop 3
	s_add_i32 s101, s100, 1
	v_mul_u32_u24_e32 v6, s100, v4
	s_nop 1
	v_writelane_b32 v255, s101, 61
	v_add_u32_e32 v4, v6, v4
	s_waitcnt vmcnt(0)
	v_readfirstlane_b32 s6, v5
	v_add_u32_e32 v7, s6, v2
	v_add_u32_e32 v5, 1, v7
	v_mov_b32_e32 v2, s100
	v_cmp_ne_u32_e32 vcc, v5, v4
	s_and_saveexec_b64 s[6:7], vcc
	s_xor_b64 s[6:7], exec, s[6:7]
	s_cbranch_execz .LBB0_55
	v_readlane_b32 s12, v252, 62
	v_readlane_b32 s13, v252, 63
	s_waitcnt lgkmcnt(0)
	s_nop 3
	global_load_dword v1, v3, s[12:13] sc1
	s_waitcnt vmcnt(0)
	v_cmp_eq_u32_e32 vcc, v1, v2
	s_and_saveexec_b64 s[12:13], vcc
	s_cbranch_execz .LBB0_54
	s_mov_b32 s24, 1
	s_mov_b64 s[14:15], 0
	s_branch .LBB0_45

.LBB0_58:
	s_or_b64 exec, exec, s[12:13]
	v_mul_u32_u24_e32 v5, s100, v1
	s_mov_b64 s[12:13], -1
	v_add_u32_e32 v1, v5, v1
	s_waitcnt vmcnt(0)
	v_readfirstlane_b32 s6, v4
	v_add_u32_e32 v2, s6, v2
	v_add_u32_e32 v6, 1, v2
	v_mov_b32_e32 v2, s100
	v_cmp_ne_u32_e32 vcc, v6, v1
	v_mov_b64_e32 v[4:5], s[76:77]
	s_and_saveexec_b64 s[6:7], vcc
	s_cbranch_execz .LBB0_70
	global_load_dword v1, v3, s[76:77] sc1
	s_mov_b64 s[14:15], 0
	s_waitcnt vmcnt(0)
	v_cmp_eq_u32_e32 vcc, v1, v2
	s_and_saveexec_b64 s[12:13], vcc
	s_cbranch_execz .LBB0_69
	s_mov_b32 s24, 1
	s_branch .LBB0_62
